# GEMM1 column rotation table 0x3ea40 (another min-max balanced assignment of gelu/silu/plain/transposed tiles over the four workgroup classes)
# speedup vs baseline: 1.0024x; 1.0024x over previous
.LBB0_263:
	s_add_i32 s58, s58, 1
	s_mul_i32 s0, s58, s31
	s_mul_hi_u32 s1, s58, s3
	s_add_i32 s1, s1, s0
	s_mul_i32 s0, s58, s3
	s_add_u32 s14, s0, s2
	s_addc_u32 s15, s1, s7
	v_mov_b64_e32 v[2:3], 0x900
	v_cmp_lt_i64_e64 s[40:41], s[14:15], v[2:3]
	v_mov_b64_e32 v[2:3], 0x8ff
	v_cmp_gt_i64_e32 vcc, s[14:15], v[2:3]
	s_cbranch_vccnz .LBB0_265
	s_ashr_i32 s0, s14, 31
	s_lshr_b32 s0, s0, 29
	s_add_i32 s0, s14, s0
	s_ashr_i32 s1, s0, 3
	s_and_b32 s0, s0, -8
	s_sub_i32 s0, s14, s0
	s_cmp_lt_i32 s0, 0
	s_cselect_b32 s14, s83, 0x120
	s_mul_i32 s0, s0, s14
	s_add_i32 s0, s0, s1
	s_mul_hi_i32 s1, s0, 0x2aaaaaab
	s_lshr_b32 s14, s1, 31
	s_ashr_i32 s1, s1, 4
	s_add_i32 s1, s1, s14
	s_lshl_b32 s14, s1, 3
	s_sub_i32 s15, 0xc0, s14
	s_min_i32 s15, s15, 8
	s_abs_i32 s16, s15
	v_cvt_f32_u32_e32 v2, s16
	s_sub_i32 s35, 0, s16
	s_mulk_i32 s1, 0x60
	s_sub_i32 s0, s0, s1
	v_rcp_iflag_f32_e32 v2, v2
	s_abs_i32 s1, s0
	s_xor_b32 s17, s0, s15
	s_ashr_i32 s17, s17, 31
	v_mul_f32_e32 v2, 0x4f7ffffe, v2
	v_cvt_u32_f32_e32 v2, v2
	s_nop 0
	v_readfirstlane_b32 s38, v2
	s_mul_i32 s35, s35, s38
	s_mul_hi_u32 s35, s38, s35
	s_add_i32 s38, s38, s35
	s_mul_hi_u32 s35, s1, s38
	s_mul_i32 s38, s35, s16
	s_sub_i32 s1, s1, s38
	s_add_i32 s39, s35, 1
	s_sub_i32 s38, s1, s16
	s_cmp_ge_u32 s1, s16
	s_cselect_b32 s35, s39, s35
	s_cselect_b32 s1, s38, s1
	s_add_i32 s38, s35, 1
	s_cmp_ge_u32 s1, s16
	s_cselect_b32 s1, s38, s35
	s_xor_b32 s1, s1, s17
	s_sub_i32 s48, s1, s17
	s_mul_i32 s1, s48, s15
	s_sub_i32 s0, s0, s1
	s_add_i32 s50, s14, s0
	s_lshl_b32 s1, s58, 1
	s_lshr_b32 s1, 0x3ea40, s1
	s_add_i32 s1, s1, s48
	s_and_b32 s1, s1, 3
	s_and_b32 s48, s48, -4
	s_or_b32 s48, s48, s1
